# peeled_iteration_relaxed_waits
# baseline (speedup 1.0000x reference)
; #define PG8_STAGE(bufoff, gbase, voff) do { _Pragma("unroll") for (int _i = 0; _i < 2; ++_i) \
;         __builtin_amdgcn_global_load_lds((const unsigned*)((const char*)(gbase) + (voff)[_i]), (LAS unsigned*)(lds + (bufoff) + ldsw + _i * 8192), 16, 0, 0); } while (0)
; #define PG8_LDA(dst, b, h) do { _Pragma("unroll") for (int m = 0; m < 4; ++m) _Pragma("unroll") for (int k = 0; k < 2; ++k) dst[m][k] = *(const LAS bf16x8*)(lds + PG8_SA(b, h) + aoff + m * 2048 + k * 1024); } while (0)
; #define PG8_LDB(dst, b, h) do { _Pragma("unroll") for (int n = 0; n < 2; ++n) _Pragma("unroll") for (int k = 0; k < 2; ++k) dst[n][k] = *(const LAS bf16x8*)(lds + PG8_SB(b, h) + boff + n * 2048 + k * 1024); } while (0)
; #define PG8_MMA(ai, bj, At, Bt) do { __builtin_amdgcn_s_setprio(1); _Pragma("unroll") for (int m = 0; m < 4; ++m) _Pragma("unroll") for (int n = 0; n < 2; ++n) _Pragma("unroll") for (int k = 0; k < 2; ++k) \
;         acc[ai][bj][m][n] = __builtin_amdgcn_mfma_f32_16x16x32_bf16(Bt[n][k], At[m][k], acc[ai][bj][m][n], 0, 0, 0); __builtin_amdgcn_s_setprio(0); } while (0)
; #define PG8_WAIT_V(n) asm volatile("s_waitcnt vmcnt(" #n ")" ::: "memory")
; #define PG8_WAIT_L(n) asm volatile("s_waitcnt lgkmcnt(" #n ")" ::: "memory")
; #define PG8_BAR __builtin_amdgcn_s_barrier()
; #define PG8_SCHED __builtin_amdgcn_sched_barrier(0)
; template <class Epi, class Sched>
; __device__ __forceinline__ void gemm_phase(LAS unsigned char* lds, const Sched& S, const Epi& E, bool natural = false) {
;     ...
;             PG8_LDB(B0, 0, 0); PG8_LDB(B1, 0, 1); PG8_SCHED; PG8_LDA(At, 0, 0); PG8_STAGE(PG8_SA(1, 1), a1 + hstep, voffA);
;             PG8_WAIT_V(8); PG8_WAIT_L(0); PG8_BAR; PG8_MMA(0, 0, At, B0); PG8_MMA(0, 1, At, B1); PG8_BAR; PG8_SCHED;
;             PG8_LDA(At, 0, 1); PG8_STAGE(PG8_SB(0, 0), b2, voffB0); PG8_STAGE(PG8_SB(0, 1), b2, voffB1); PG8_STAGE(PG8_SA(0, 0), a2, voffA);
;             PG8_WAIT_V(8); PG8_WAIT_L(0); PG8_BAR; PG8_MMA(1, 0, At, B0); PG8_MMA(1, 1, At, B1); PG8_BAR; PG8_SCHED;
.LBB0_173:
	s_add_u32 s40, s40, 0x40080
	s_addc_u32 s41, s41, 0
	s_add_u32 s31, s42, 0x100
	s_addc_u32 s35, s43, 0
	s_mov_b32 s71, -2
	ds_read_b128 v[128:131], v196
	ds_read_b128 v[132:135], v196 offset:1024
	ds_read_b128 v[136:139], v196 offset:2048
	ds_read_b128 v[140:143], v196 offset:3072
	ds_read_b128 v[144:147], v197
	ds_read_b128 v[148:151], v197 offset:1024
	ds_read_b128 v[186:189], v197 offset:2048
	ds_read_b128 v[202:205], v197 offset:3072
	s_add_u32 s42, s40, 0xfffc0080
	s_addc_u32 s43, s41, -1
	s_cmp_eq_u32 s71, 12
	s_cselect_b32 s45, s1, s43
	s_cselect_b32 s44, s0, s42
	s_cselect_b32 s43, s37, s35
	s_cselect_b32 s42, s36, s31
	v_lshl_add_u64 v[238:239], s[40:41], 0, v[178:179]
	s_add_i32 m0, s39, 0xc000
	ds_read_b128 v[206:209], v198
	ds_read_b128 v[210:213], v198 offset:1024
	ds_read_b128 v[214:217], v198 offset:2048
	ds_read_b128 v[218:221], v198 offset:3072
	ds_read_b128 v[222:225], v198 offset:4096
	ds_read_b128 v[226:229], v198 offset:5120
	ds_read_b128 v[230:233], v198 offset:6144
	ds_read_b128 v[234:237], v198 offset:7168
	global_load_lds_dwordx4 v[238:239], off
	v_lshl_add_u64 v[238:239], s[40:41], 0, v[180:181]
	s_add_i32 m0, s39, 0xe000
	s_nop 0
	global_load_lds_dwordx4 v[238:239], off
	s_waitcnt vmcnt(24)
	s_waitcnt lgkmcnt(0)
	s_barrier
	s_setprio 1
	s_waitcnt lgkmcnt(0)
	v_mfma_f32_16x16x32_bf16 v[124:127], v[128:131], v[206:209], 0
	v_mfma_f32_16x16x32_bf16 v[120:123], v[136:139], v[206:209], 0
	v_mfma_f32_16x16x32_bf16 v[108:111], v[128:131], v[214:217], 0
	v_mfma_f32_16x16x32_bf16 v[104:107], v[136:139], v[214:217], 0
	v_mfma_f32_16x16x32_bf16 v[92:95], v[128:131], v[222:225], 0
	v_mfma_f32_16x16x32_bf16 v[88:91], v[136:139], v[222:225], 0
	v_mfma_f32_16x16x32_bf16 v[76:79], v[128:131], v[230:233], 0
	v_mfma_f32_16x16x32_bf16 v[72:75], v[136:139], v[230:233], 0
	v_mfma_f32_16x16x32_bf16 v[124:127], v[132:135], v[210:213], v[124:127]
	v_mfma_f32_16x16x32_bf16 v[120:123], v[140:143], v[210:213], v[120:123]
	v_mfma_f32_16x16x32_bf16 v[108:111], v[132:135], v[218:221], v[108:111]
	v_mfma_f32_16x16x32_bf16 v[104:107], v[140:143], v[218:221], v[104:107]
	v_mfma_f32_16x16x32_bf16 v[92:95], v[132:135], v[226:229], v[92:95]
	v_mfma_f32_16x16x32_bf16 v[88:91], v[140:143], v[226:229], v[88:91]
	v_mfma_f32_16x16x32_bf16 v[76:79], v[132:135], v[234:237], v[76:79]
	v_mfma_f32_16x16x32_bf16 v[72:75], v[140:143], v[234:237], v[72:75]
	s_setprio 0
	s_setprio 1
	v_mfma_f32_16x16x32_bf16 v[116:119], v[144:147], v[206:209], 0
	v_mfma_f32_16x16x32_bf16 v[112:115], v[186:189], v[206:209], 0
	v_mfma_f32_16x16x32_bf16 v[100:103], v[144:147], v[214:217], 0
	v_mfma_f32_16x16x32_bf16 v[96:99], v[186:189], v[214:217], 0
	v_mfma_f32_16x16x32_bf16 v[84:87], v[144:147], v[222:225], 0
	v_mfma_f32_16x16x32_bf16 v[80:83], v[186:189], v[222:225], 0
	v_mfma_f32_16x16x32_bf16 v[68:71], v[144:147], v[230:233], 0
	v_mfma_f32_16x16x32_bf16 v[64:67], v[186:189], v[230:233], 0
	v_mfma_f32_16x16x32_bf16 v[116:119], v[148:151], v[210:213], v[116:119]
	v_mfma_f32_16x16x32_bf16 v[112:115], v[202:205], v[210:213], v[112:115]
	v_mfma_f32_16x16x32_bf16 v[100:103], v[148:151], v[218:221], v[100:103]
	v_mfma_f32_16x16x32_bf16 v[96:99], v[202:205], v[218:221], v[96:99]
	v_mfma_f32_16x16x32_bf16 v[84:87], v[148:151], v[226:229], v[84:87]
	v_mfma_f32_16x16x32_bf16 v[80:83], v[202:205], v[226:229], v[80:83]
	v_mfma_f32_16x16x32_bf16 v[68:71], v[148:151], v[234:237], v[68:71]
	v_mfma_f32_16x16x32_bf16 v[64:67], v[202:205], v[234:237], v[64:67]
	s_setprio 0
	s_barrier
	s_add_i32 s72, s59, s33
	v_lshl_add_u64 v[238:239], s[42:43], 0, v[156:157]
	s_mov_b32 m0, s72
	ds_read_b128 v[206:209], v198 offset:16384
	ds_read_b128 v[210:213], v198 offset:17408
	ds_read_b128 v[214:217], v198 offset:18432
	ds_read_b128 v[218:221], v198 offset:19456
	ds_read_b128 v[222:225], v198 offset:20480
	ds_read_b128 v[226:229], v198 offset:21504
	ds_read_b128 v[230:233], v198 offset:22528
	ds_read_b128 v[234:237], v198 offset:23552
	global_load_lds_dwordx4 v[238:239], off
	v_lshl_add_u64 v[240:241], s[42:43], 0, v[162:163]
	s_add_i32 m0, s72, 0x2000
	s_add_i32 s72, s60, s33
	global_load_lds_dwordx4 v[240:241], off
	v_lshl_add_u64 v[242:243], s[42:43], 0, v[158:159]
	s_mov_b32 m0, s72
	v_lshl_add_u64 v[244:245], s[44:45], 0, v[160:161]
	global_load_lds_dwordx4 v[242:243], off
	v_lshl_add_u64 v[242:243], s[42:43], 0, v[164:165]
	s_add_i32 m0, s72, 0x2000
	s_nop 0
	global_load_lds_dwordx4 v[242:243], off
	v_lshl_add_u64 v[242:243], s[44:45], 0, v[154:155]
	s_mov_b32 m0, s39
	s_nop 0
	global_load_lds_dwordx4 v[242:243], off
	s_mov_b32 m0, s46
	s_nop 0
	global_load_lds_dwordx4 v[244:245], off
	s_waitcnt vmcnt(24)
	s_waitcnt lgkmcnt(0)
	s_barrier
; #define PG8_STAGE(bufoff, gbase, voff) do { _Pragma("unroll") for (int _i = 0; _i < 2; ++_i) \
;         __builtin_amdgcn_global_load_lds((const unsigned*)((const char*)(gbase) + (voff)[_i]), (LAS unsigned*)(lds + (bufoff) + ldsw + _i * 8192), 16, 0, 0); } while (0)
; #define PG8_LDA(dst, b, h) do { _Pragma("unroll") for (int m = 0; m < 4; ++m) _Pragma("unroll") for (int k = 0; k < 2; ++k) dst[m][k] = *(const LAS bf16x8*)(lds + PG8_SA(b, h) + aoff + m * 2048 + k * 1024); } while (0)
; #define PG8_LDB(dst, b, h) do { _Pragma("unroll") for (int n = 0; n < 2; ++n) _Pragma("unroll") for (int k = 0; k < 2; ++k) dst[n][k] = *(const LAS bf16x8*)(lds + PG8_SB(b, h) + boff + n * 2048 + k * 1024); } while (0)
; #define PG8_MMA(ai, bj, At, Bt) do { __builtin_amdgcn_s_setprio(1); _Pragma("unroll") for (int m = 0; m < 4; ++m) _Pragma("unroll") for (int n = 0; n < 2; ++n) _Pragma("unroll") for (int k = 0; k < 2; ++k) \
;         acc[ai][bj][m][n] = __builtin_amdgcn_mfma_f32_16x16x32_bf16(Bt[n][k], At[m][k], acc[ai][bj][m][n], 0, 0, 0); __builtin_amdgcn_s_setprio(0); } while (0)
; #define PG8_WAIT_V(n) asm volatile("s_waitcnt vmcnt(" #n ")" ::: "memory")
; #define PG8_WAIT_L(n) asm volatile("s_waitcnt lgkmcnt(" #n ")" ::: "memory")
; #define PG8_BAR __builtin_amdgcn_s_barrier()
; #define PG8_SCHED __builtin_amdgcn_sched_barrier(0)
; template <class Epi, class Sched>
; __device__ __forceinline__ void gemm_phase(LAS unsigned char* lds, const Sched& S, const Epi& E, bool natural = false) {
;     ...
;             PG8_WAIT_V(8); PG8_WAIT_L(0); PG8_BAR; PG8_MMA(1, 0, At, B0); PG8_MMA(1, 1, At, B1); PG8_BAR; PG8_SCHED;
;             PG8_LDB(B0, 1, 0); PG8_LDB(B1, 1, 1); PG8_SCHED; PG8_LDA(At, 1, 0); PG8_STAGE(PG8_SA(0, 1), a2 + hstep, voffA);
;             PG8_WAIT_V(8); PG8_WAIT_L(0); PG8_BAR; PG8_MMA(0, 0, At, B0); PG8_MMA(0, 1, At, B1); PG8_BAR; PG8_SCHED;
;             PG8_LDA(At, 1, 1); PG8_STAGE(PG8_SB(1, 0), b3, voffB0); PG8_STAGE(PG8_SB(1, 1), b3, voffB1); PG8_STAGE(PG8_SA(1, 0), a3, voffA);
	s_setprio 1
	s_waitcnt lgkmcnt(0)
	v_mfma_f32_16x16x32_bf16 v[60:63], v[128:131], v[206:209], 0
	v_mfma_f32_16x16x32_bf16 v[56:59], v[136:139], v[206:209], 0
	v_mfma_f32_16x16x32_bf16 v[44:47], v[128:131], v[214:217], 0
	v_mfma_f32_16x16x32_bf16 v[40:43], v[136:139], v[214:217], 0
	v_mfma_f32_16x16x32_bf16 v[28:31], v[128:131], v[222:225], 0
	v_mfma_f32_16x16x32_bf16 v[24:27], v[136:139], v[222:225], 0
	v_mfma_f32_16x16x32_bf16 v[12:15], v[128:131], v[230:233], 0
	v_mfma_f32_16x16x32_bf16 v[8:11], v[136:139], v[230:233], 0
	v_mfma_f32_16x16x32_bf16 v[60:63], v[132:135], v[210:213], v[60:63]
	v_mfma_f32_16x16x32_bf16 v[56:59], v[140:143], v[210:213], v[56:59]
	v_mfma_f32_16x16x32_bf16 v[44:47], v[132:135], v[218:221], v[44:47]
	v_mfma_f32_16x16x32_bf16 v[40:43], v[140:143], v[218:221], v[40:43]
	v_mfma_f32_16x16x32_bf16 v[28:31], v[132:135], v[226:229], v[28:31]
	v_mfma_f32_16x16x32_bf16 v[24:27], v[140:143], v[226:229], v[24:27]
	v_mfma_f32_16x16x32_bf16 v[12:15], v[132:135], v[234:237], v[12:15]
	v_mfma_f32_16x16x32_bf16 v[8:11], v[140:143], v[234:237], v[8:11]
	s_setprio 0
	s_setprio 1
	v_mfma_f32_16x16x32_bf16 v[52:55], v[144:147], v[206:209], 0
	v_mfma_f32_16x16x32_bf16 v[48:51], v[186:189], v[206:209], 0
	v_mfma_f32_16x16x32_bf16 v[36:39], v[144:147], v[214:217], 0
	v_mfma_f32_16x16x32_bf16 v[32:35], v[186:189], v[214:217], 0
	v_mfma_f32_16x16x32_bf16 v[20:23], v[144:147], v[222:225], 0
	v_mfma_f32_16x16x32_bf16 v[16:19], v[186:189], v[222:225], 0
	v_mfma_f32_16x16x32_bf16 v[4:7], v[144:147], v[230:233], 0
	v_mfma_f32_16x16x32_bf16 v[0:3], v[186:189], v[230:233], 0
	v_mfma_f32_16x16x32_bf16 v[52:55], v[148:151], v[210:213], v[52:55]
	v_mfma_f32_16x16x32_bf16 v[48:51], v[202:205], v[210:213], v[48:51]
	v_mfma_f32_16x16x32_bf16 v[36:39], v[148:151], v[218:221], v[36:39]
	v_mfma_f32_16x16x32_bf16 v[32:35], v[202:205], v[218:221], v[32:35]
	v_mfma_f32_16x16x32_bf16 v[20:23], v[148:151], v[226:229], v[20:23]
	v_mfma_f32_16x16x32_bf16 v[16:19], v[202:205], v[226:229], v[16:19]
	v_mfma_f32_16x16x32_bf16 v[4:7], v[148:151], v[234:237], v[4:7]
	v_mfma_f32_16x16x32_bf16 v[0:3], v[202:205], v[234:237], v[0:3]
	s_setprio 0
	s_barrier
	s_add_i32 s72, 0, 0x18000
	s_add_i32 s73, 0, 0x1c000
	v_add_u32_e32 v140, s72, v192
	v_add_u32_e32 v166, s73, v192
	ds_read_b128 v[128:131], v140
	ds_read_b128 v[132:135], v140 offset:1024
	ds_read_b128 v[136:139], v140 offset:2048
	ds_read_b128 v[140:143], v140 offset:3072
	ds_read_b128 v[144:147], v166
	ds_read_b128 v[148:151], v166 offset:1024
	ds_read_b128 v[186:189], v166 offset:2048
	ds_read_b128 v[202:205], v166 offset:3072
	s_add_u32 s44, s44, 0x40000
	s_addc_u32 s45, s45, 0
	s_mov_b32 m0, s47
	v_lshl_add_u64 v[246:247], s[44:45], 0, v[154:155]
	ds_read_b128 v[206:209], v198 offset:32768
	ds_read_b128 v[210:213], v198 offset:33792
	ds_read_b128 v[214:217], v198 offset:34816
	ds_read_b128 v[218:221], v198 offset:35840
	ds_read_b128 v[222:225], v198 offset:36864
	ds_read_b128 v[226:229], v198 offset:37888
	ds_read_b128 v[230:233], v198 offset:38912
	ds_read_b128 v[234:237], v198 offset:39936
	global_load_lds_dwordx4 v[246:247], off
	v_lshl_add_u64 v[246:247], s[44:45], 0, v[160:161]
	s_mov_b32 m0, s49
	s_nop 0
	global_load_lds_dwordx4 v[246:247], off
	s_waitcnt vmcnt(8)
	s_waitcnt lgkmcnt(0)
	s_barrier
	s_setprio 1
	s_waitcnt lgkmcnt(0)
	v_mfma_f32_16x16x32_bf16 v[124:127], v[128:131], v[206:209], v[124:127]
	v_mfma_f32_16x16x32_bf16 v[120:123], v[136:139], v[206:209], v[120:123]
	v_mfma_f32_16x16x32_bf16 v[108:111], v[128:131], v[214:217], v[108:111]
	v_mfma_f32_16x16x32_bf16 v[104:107], v[136:139], v[214:217], v[104:107]
	v_mfma_f32_16x16x32_bf16 v[92:95], v[128:131], v[222:225], v[92:95]
	v_mfma_f32_16x16x32_bf16 v[88:91], v[136:139], v[222:225], v[88:91]
	v_mfma_f32_16x16x32_bf16 v[76:79], v[128:131], v[230:233], v[76:79]
	v_mfma_f32_16x16x32_bf16 v[72:75], v[136:139], v[230:233], v[72:75]
	v_mfma_f32_16x16x32_bf16 v[124:127], v[132:135], v[210:213], v[124:127]
	v_mfma_f32_16x16x32_bf16 v[120:123], v[140:143], v[210:213], v[120:123]
	v_mfma_f32_16x16x32_bf16 v[108:111], v[132:135], v[218:221], v[108:111]
	v_mfma_f32_16x16x32_bf16 v[104:107], v[140:143], v[218:221], v[104:107]
	v_mfma_f32_16x16x32_bf16 v[92:95], v[132:135], v[226:229], v[92:95]
	v_mfma_f32_16x16x32_bf16 v[88:91], v[140:143], v[226:229], v[88:91]
	v_mfma_f32_16x16x32_bf16 v[76:79], v[132:135], v[234:237], v[76:79]
	v_mfma_f32_16x16x32_bf16 v[72:75], v[140:143], v[234:237], v[72:75]
	s_setprio 0
	s_setprio 1
	v_mfma_f32_16x16x32_bf16 v[116:119], v[144:147], v[206:209], v[116:119]
	v_mfma_f32_16x16x32_bf16 v[112:115], v[186:189], v[206:209], v[112:115]
	v_mfma_f32_16x16x32_bf16 v[100:103], v[144:147], v[214:217], v[100:103]
	v_mfma_f32_16x16x32_bf16 v[96:99], v[186:189], v[214:217], v[96:99]
	v_mfma_f32_16x16x32_bf16 v[84:87], v[144:147], v[222:225], v[84:87]
	v_mfma_f32_16x16x32_bf16 v[80:83], v[186:189], v[222:225], v[80:83]
	v_mfma_f32_16x16x32_bf16 v[68:71], v[144:147], v[230:233], v[68:71]
	v_mfma_f32_16x16x32_bf16 v[64:67], v[186:189], v[230:233], v[64:67]
	v_mfma_f32_16x16x32_bf16 v[116:119], v[148:151], v[210:213], v[116:119]
	v_mfma_f32_16x16x32_bf16 v[112:115], v[202:205], v[210:213], v[112:115]
	v_mfma_f32_16x16x32_bf16 v[100:103], v[148:151], v[218:221], v[100:103]
	v_mfma_f32_16x16x32_bf16 v[96:99], v[202:205], v[218:221], v[96:99]
	v_mfma_f32_16x16x32_bf16 v[84:87], v[148:151], v[226:229], v[84:87]
	v_mfma_f32_16x16x32_bf16 v[80:83], v[202:205], v[226:229], v[80:83]
	v_mfma_f32_16x16x32_bf16 v[68:71], v[148:151], v[234:237], v[68:71]
	v_mfma_f32_16x16x32_bf16 v[64:67], v[202:205], v[234:237], v[64:67]
	s_setprio 0
	s_barrier
; #define PG8_STAGE(bufoff, gbase, voff) do { _Pragma("unroll") for (int _i = 0; _i < 2; ++_i) \
;         __builtin_amdgcn_global_load_lds((const unsigned*)((const char*)(gbase) + (voff)[_i]), (LAS unsigned*)(lds + (bufoff) + ldsw + _i * 8192), 16, 0, 0); } while (0)
; #define PG8_LDA(dst, b, h) do { _Pragma("unroll") for (int m = 0; m < 4; ++m) _Pragma("unroll") for (int k = 0; k < 2; ++k) dst[m][k] = *(const LAS bf16x8*)(lds + PG8_SA(b, h) + aoff + m * 2048 + k * 1024); } while (0)
; #define PG8_MMA(ai, bj, At, Bt) do { __builtin_amdgcn_s_setprio(1); _Pragma("unroll") for (int m = 0; m < 4; ++m) _Pragma("unroll") for (int n = 0; n < 2; ++n) _Pragma("unroll") for (int k = 0; k < 2; ++k) \
;         acc[ai][bj][m][n] = __builtin_amdgcn_mfma_f32_16x16x32_bf16(Bt[n][k], At[m][k], acc[ai][bj][m][n], 0, 0, 0); __builtin_amdgcn_s_setprio(0); } while (0)
; #define PG8_WAIT_V(n) asm volatile("s_waitcnt vmcnt(" #n ")" ::: "memory")
; #define PG8_WAIT_L(n) asm volatile("s_waitcnt lgkmcnt(" #n ")" ::: "memory")
; #define PG8_BAR __builtin_amdgcn_s_barrier()
; #define PG8_SCHED __builtin_amdgcn_sched_barrier(0)
; template <class Epi, class Sched>
; __device__ __forceinline__ void gemm_phase(LAS unsigned char* lds, const Sched& S, const Epi& E, bool natural = false) {
;     ...
;             PG8_LDA(At, 1, 1); PG8_STAGE(PG8_SB(1, 0), b3, voffB0); PG8_STAGE(PG8_SB(1, 1), b3, voffB1); PG8_STAGE(PG8_SA(1, 0), a3, voffA);
;             PG8_WAIT_V(8); PG8_WAIT_L(0); PG8_BAR; PG8_MMA(1, 0, At, B0); PG8_MMA(1, 1, At, B1); PG8_BAR; PG8_SCHED;
;         }
	s_add_u32 s42, s42, 0x80
	s_addc_u32 s43, s43, 0
	s_add_i32 s44, s72, s33
	v_lshl_add_u64 v[238:239], v[238:239], 0, s[12:13]
	s_mov_b32 m0, s44
	ds_read_b128 v[206:209], v198 offset:49152
	ds_read_b128 v[210:213], v198 offset:50176
	ds_read_b128 v[214:217], v198 offset:51200
	ds_read_b128 v[218:221], v198 offset:52224
	ds_read_b128 v[222:225], v198 offset:53248
	ds_read_b128 v[226:229], v198 offset:54272
	ds_read_b128 v[230:233], v198 offset:55296
	ds_read_b128 v[234:237], v198 offset:56320
	global_load_lds_dwordx4 v[238:239], off
	v_lshl_add_u64 v[238:239], v[240:241], 0, s[12:13]
	s_add_i32 m0, s44, 0x2000
	s_add_i32 s44, s73, s33
	global_load_lds_dwordx4 v[238:239], off
	v_lshl_add_u64 v[238:239], s[42:43], 0, v[158:159]
	s_mov_b32 m0, s44
	s_nop 0
	global_load_lds_dwordx4 v[238:239], off
	v_lshl_add_u64 v[238:239], s[42:43], 0, v[164:165]
	s_add_i32 m0, s44, 0x2000
	s_nop 0
	global_load_lds_dwordx4 v[238:239], off
	v_lshl_add_u64 v[238:239], v[242:243], 0, s[12:13]
	s_mov_b32 m0, s51
	s_nop 0
	global_load_lds_dwordx4 v[238:239], off
	v_lshl_add_u64 v[238:239], v[244:245], 0, s[12:13]
	s_mov_b32 m0, s52
	s_nop 0
	global_load_lds_dwordx4 v[238:239], off
	s_waitcnt vmcnt(8)
	s_waitcnt lgkmcnt(0)
	s_barrier
	s_setprio 1
	s_waitcnt lgkmcnt(0)
	v_mfma_f32_16x16x32_bf16 v[60:63], v[128:131], v[206:209], v[60:63]
	v_mfma_f32_16x16x32_bf16 v[56:59], v[136:139], v[206:209], v[56:59]
	v_mfma_f32_16x16x32_bf16 v[44:47], v[128:131], v[214:217], v[44:47]
	v_mfma_f32_16x16x32_bf16 v[40:43], v[136:139], v[214:217], v[40:43]
	v_mfma_f32_16x16x32_bf16 v[28:31], v[128:131], v[222:225], v[28:31]
	v_mfma_f32_16x16x32_bf16 v[24:27], v[136:139], v[222:225], v[24:27]
	v_mfma_f32_16x16x32_bf16 v[12:15], v[128:131], v[230:233], v[12:15]
	v_mfma_f32_16x16x32_bf16 v[8:11], v[136:139], v[230:233], v[8:11]
	v_mfma_f32_16x16x32_bf16 v[60:63], v[132:135], v[210:213], v[60:63]
	v_mfma_f32_16x16x32_bf16 v[56:59], v[140:143], v[210:213], v[56:59]
	v_mfma_f32_16x16x32_bf16 v[44:47], v[132:135], v[218:221], v[44:47]
	v_mfma_f32_16x16x32_bf16 v[40:43], v[140:143], v[218:221], v[40:43]
	v_mfma_f32_16x16x32_bf16 v[28:31], v[132:135], v[226:229], v[28:31]
	v_mfma_f32_16x16x32_bf16 v[24:27], v[140:143], v[226:229], v[24:27]
	v_mfma_f32_16x16x32_bf16 v[12:15], v[132:135], v[234:237], v[12:15]
	v_mfma_f32_16x16x32_bf16 v[8:11], v[140:143], v[234:237], v[8:11]
	s_setprio 0
	s_setprio 1
	v_mfma_f32_16x16x32_bf16 v[52:55], v[144:147], v[206:209], v[52:55]
	v_mfma_f32_16x16x32_bf16 v[48:51], v[186:189], v[206:209], v[48:51]
	v_mfma_f32_16x16x32_bf16 v[36:39], v[144:147], v[214:217], v[36:39]
	v_mfma_f32_16x16x32_bf16 v[32:35], v[186:189], v[214:217], v[32:35]
	v_mfma_f32_16x16x32_bf16 v[20:23], v[144:147], v[222:225], v[20:23]
	v_mfma_f32_16x16x32_bf16 v[16:19], v[186:189], v[222:225], v[16:19]
	v_mfma_f32_16x16x32_bf16 v[4:7], v[144:147], v[230:233], v[4:7]
	v_mfma_f32_16x16x32_bf16 v[0:3], v[186:189], v[230:233], v[0:3]
	v_mfma_f32_16x16x32_bf16 v[52:55], v[148:151], v[210:213], v[52:55]
	v_mfma_f32_16x16x32_bf16 v[48:51], v[202:205], v[210:213], v[48:51]
	v_mfma_f32_16x16x32_bf16 v[36:39], v[148:151], v[218:221], v[36:39]
	v_mfma_f32_16x16x32_bf16 v[32:35], v[202:205], v[218:221], v[32:35]
	v_mfma_f32_16x16x32_bf16 v[20:23], v[148:151], v[226:229], v[20:23]
	v_mfma_f32_16x16x32_bf16 v[16:19], v[202:205], v[226:229], v[16:19]
	v_mfma_f32_16x16x32_bf16 v[4:7], v[148:151], v[234:237], v[4:7]
	v_mfma_f32_16x16x32_bf16 v[0:3], v[202:205], v[234:237], v[0:3]
	s_setprio 0
	s_barrier
	s_add_i32 s71, s71, 2
	s_add_u32 s40, s40, 0x100
	s_addc_u32 s41, s41, 0
	s_add_u32 s31, s31, 0x100
	s_addc_u32 s35, s35, 0
	s_cmp_gt_u32 s71, 13
	s_cbranch_scc0 .LBB0_174
